# X1 + GQA attention Q-prep: the 8 serialised gain-vector load pairs prefetched 5 deep into dead tile-loop fragment registers with counted waits
# speedup vs baseline: 1.0054x; 1.0039x over previous
; __device__ __forceinline__ float bf_lo(unsigned u) { return __uint_as_float(u << 16); }
; __device__ __forceinline__ float bf_hi(unsigned u) { return __uint_as_float(u & 0xffff0000u); }
; #define KDMA(b, k0) do { const GAS char* _g = (const GAS char*)Kh + (size_t)(k0) * (size_t)ldk * 2; _Pragma("unroll") for (int _i = 0; _i < 2; ++_i) \
;     __builtin_amdgcn_global_load_lds((const GAS unsigned*)(_g + kso[_i]), (LAS unsigned*)(K_lds + (b) * SHM_K + (_i * 8 + wid) * 1024), 16, 0, 0); } while (0)
; template <bool NATM, int QN> ...
;     ...
;   for (int i = 0; i < 2; ++i) { const int B = i * 8 + wid;
;     const int row = 4 * B + (lane >> 4); kso[i] = (unsigned)(row * ldk + (((lane & 15) ^ (row & 7)) << 3)) * 2u;
;     const int S = 2 * B + (lane >> 5), kk = (S >> 2) * 8 + ((lane >> 2) & 7), kt = (kk & ~0xC) | ((kk & 4) << 1) | ((kk & 8) >> 1), c = (S & 3) * 32 + (lane & 3) * 8; vso[i] = (unsigned)(kt * ldk + c) * 2u; }
;     ...
;   KDMA(0, KROW(0)); VDMA(0, KROW(0)); KDMA(1, KROW(1));
;   const gb16* Qw = Qb + (long)(wid * QBLK + r32) * ldq + hi * 8;
; #pragma unroll
;   for (int d0 = 0; d0 < 8; ++d0) qr[d0] = *(const gbf16x8*)(Qw + d0 * 16);
;   if constexpr (QN != 0) {
;     float ss = 0.f;
; #pragma unroll
;     for (int d0 = 0; d0 < 8; ++d0) { const u32x4 w = *reinterpret_cast<const u32x4*>(&qr[d0]);
;       ss += (bf_lo(w.x) * bf_lo(w.x) + bf_hi(w.x) * bf_hi(w.x)) + (bf_lo(w.y) * bf_lo(w.y) + bf_hi(w.y) * bf_hi(w.y)) + (bf_lo(w.z) * bf_lo(w.z) + bf_hi(w.z) * bf_hi(w.z)) + (bf_lo(w.w) * bf_lo(w.w) + bf_hi(w.w) * bf_hi(w.w)); }
;     { auto rr = __builtin_amdgcn_permlane32_swap(__float_as_uint(ss), __float_as_uint(ss), false, false); ss = __uint_as_float(rr[0]) + __uint_as_float(rr[1]); }
; __device__ __forceinline__ void phase_attn_gqa(Frame& F, char* lds) {
;     ...
;         else { const int v = u - 512, b = v >> 4, h = v & 15, kvh = h >> 2; const size_t qrow = (size_t)b * RB;
;             att::attn_unit<false, 1>(Q + qrow * DM + h * HD, Kp + (size_t)b * RB * 512 + kvh * HD, Vp + (size_t)b * RB * 512 + kvh * HD, PO + qrow * DM + h * HD, DM, 512, DM, CTXL / 64, 0, CTXL / 64, lds, 0, 0, gqn, rope, 0, F.wave); }
.LBB0_415:
	s_cmpk_gt_i32 s73, 0x1ff
	s_mov_b64 s[2:3], -1
	s_waitcnt vmcnt(0)
	s_barrier
	s_cbranch_scc0 .LBB0_434
	s_add_i32 s0, s73, 0xfffffe00
	s_lshr_b32 s2, s0, 4
	s_mul_hi_u32 s1, s2, 0x880000
	s_mul_i32 s0, s2, 0x880000
	s_and_b32 s18, s73, 15
	s_lshl_b64 s[50:51], s[0:1], 1
	s_add_u32 s0, s9, s50
	s_addc_u32 s1, s10, s51
	s_lshl_b32 s3, s18, 8
	s_add_u32 s6, s0, s3
	s_addc_u32 s7, s1, 0
	s_mul_hi_u32 s0, s2, 0x440000
	s_mul_i32 s2, s2, 0x440000
	s_add_u32 s1, s11, s2
	s_addc_u32 s3, s12, s0
	s_lshl_b32 s4, s73, 6
	s_and_b32 s19, s4, 0x300
	s_add_u32 s4, s1, s19
	v_mbcnt_lo_u32_b32 v167, -1, 0
	v_mbcnt_hi_u32_b32 v167, -1, v167
	s_addc_u32 s5, s3, 0
	v_add_u32_e32 v0, s8, v167
	v_bfe_u32 v166, v167, 4, 2
	v_and_b32_e32 v1, 15, v167
	v_bfe_u32 v2, v0, 2, 2
	v_lshrrev_b32_e32 v0, 1, v0
	v_or_b32_e32 v3, s30, v166
	s_add_u32 s1, s13, s2
	v_bfe_u32 v150, v167, 5, 1
	v_and_or_b32 v0, v0, 8, v2
	v_lshlrev_b32_e32 v4, 10, v3
	v_bitop3_b32 v3, v3, v1, 7 bitop3:0x6c
	s_addc_u32 s2, s14, s0
	v_lshlrev_b32_e32 v8, 4, v167
	v_lshl_or_b32 v160, v3, 4, v4
	v_or_b32_e32 v3, s31, v0
	v_or_b32_e32 v4, s44, v150
	s_add_u32 s0, s1, s19
	v_and_b32_e32 v2, 48, v8
	v_lshlrev_b32_e32 v4, 6, v4
	v_lshlrev_b32_e32 v3, 10, v3
	s_addc_u32 s1, s2, 0
	v_or3_b32 v146, v3, v4, v2
	v_or_b32_e32 v3, s45, v166
	s_add_i32 s19, s66, 0
	v_lshlrev_b32_e32 v4, 10, v3
	v_bitop3_b32 v1, v3, v1, 7 bitop3:0x6c
	s_add_i32 s2, s19, 0x8000
	v_lshl_or_b32 v96, v1, 4, v4
	v_or_b32_e32 v0, s64, v0
	v_or_b32_e32 v1, s65, v150
	s_mov_b32 m0, s2
	s_add_i32 s3, s19, 0xa000
	v_lshlrev_b32_e32 v1, 6, v1
	v_lshlrev_b32_e32 v0, 10, v0
	v_and_b32_e32 v151, 31, v167
	global_load_lds_dwordx4 v160, s[4:5]
	s_mov_b32 m0, s3
	s_add_i32 s27, s19, 0x2000
	v_or3_b32 v148, v0, v1, v2
	global_load_lds_dwordx4 v96, s[4:5]
	s_mov_b32 m0, s19
	s_add_u32 s20, s4, 0x10000
	v_or_b32_e32 v0, s40, v151
	global_load_lds_dwordx4 v146, s[0:1]
	s_mov_b32 m0, s27
	s_addc_u32 s21, s5, 0
	s_add_i32 s52, s19, 0xc000
	v_ashrrev_i32_e32 v1, 31, v0
	global_load_lds_dwordx4 v148, s[0:1]
	s_mov_b32 m0, s52
	s_add_i32 s48, s19, 0xe000
	v_lshlrev_b64 v[0:1], 12, v[0:1]
	global_load_lds_dwordx4 v160, s[20:21]
	s_mov_b32 m0, s48
	v_lshl_add_u64 v[0:1], s[6:7], 0, v[0:1]
	v_lshlrev_b32_e32 v144, 4, v150
	v_mov_b32_e32 v145, v161
	global_load_lds_dwordx4 v96, s[20:21]
	v_lshl_add_u64 v[0:1], v[0:1], 0, v[144:145]
	global_load_dwordx4 v[4:7], v[0:1], off
	global_load_dwordx4 v[10:13], v[0:1], off offset:32
	global_load_dwordx4 v[14:17], v[0:1], off offset:64
	global_load_dwordx4 v[18:21], v[0:1], off offset:96
	global_load_dwordx4 v[22:25], v[0:1], off offset:128
	global_load_dwordx4 v[74:77], v[0:1], off offset:160
	global_load_dwordx4 v[78:81], v[0:1], off offset:192
	s_nop 0
	global_load_dwordx4 v[0:3], v[0:1], off offset:224
	v_and_b32_e32 v97, 63, v167
	s_cmp_lg_u32 0, -1
	s_cselect_b32 s6, 0, 0
	s_mov_b32 m0, s2
	s_waitcnt vmcnt(0)
	v_and_b32_e32 v66, 0xffff0000, v4
	v_and_b32_e32 v68, 0xffff0000, v5
	v_lshlrev_b32_e32 v67, 16, v4
	v_mul_f32_e32 v4, v66, v66
	v_lshlrev_b32_e32 v69, 16, v5
	v_mul_f32_e32 v5, v68, v68
	v_fmac_f32_e32 v4, v67, v67
	v_fmac_f32_e32 v5, v69, v69
	v_and_b32_e32 v70, 0xffff0000, v6
	v_add_f32_e32 v4, v4, v5
	v_lshlrev_b32_e32 v71, 16, v6
	v_mul_f32_e32 v5, v70, v70
	v_fmac_f32_e32 v5, v71, v71
	v_and_b32_e32 v72, 0xffff0000, v7
	v_add_f32_e32 v4, v5, v4
	v_lshlrev_b32_e32 v73, 16, v7
	v_mul_f32_e32 v5, v72, v72
	v_fmac_f32_e32 v5, v73, v73
	v_and_b32_e32 v58, 0xffff0000, v10
	v_and_b32_e32 v60, 0xffff0000, v11
	v_add_f32_e32 v4, v5, v4
	v_lshlrev_b32_e32 v59, 16, v10
	v_mul_f32_e32 v5, v58, v58
	v_lshlrev_b32_e32 v61, 16, v11
	v_mul_f32_e32 v6, v60, v60
	v_fmac_f32_e32 v5, v59, v59
	v_fmac_f32_e32 v6, v61, v61
	v_and_b32_e32 v62, 0xffff0000, v12
	v_add_f32_e32 v5, v5, v6
	v_lshlrev_b32_e32 v63, 16, v12
	v_mul_f32_e32 v6, v62, v62
	v_fmac_f32_e32 v6, v63, v63
	v_and_b32_e32 v64, 0xffff0000, v13
	v_add_f32_e32 v5, v6, v5
	v_lshlrev_b32_e32 v65, 16, v13
	v_mul_f32_e32 v6, v64, v64
	v_fmac_f32_e32 v6, v65, v65
	v_add_f32_e32 v5, v6, v5
	v_and_b32_e32 v50, 0xffff0000, v14
	v_and_b32_e32 v52, 0xffff0000, v15
	v_add_f32_e32 v4, v4, v5
	v_lshlrev_b32_e32 v51, 16, v14
	v_mul_f32_e32 v5, v50, v50
	v_lshlrev_b32_e32 v53, 16, v15
	v_mul_f32_e32 v6, v52, v52
	v_fmac_f32_e32 v5, v51, v51
	v_fmac_f32_e32 v6, v53, v53
	v_and_b32_e32 v54, 0xffff0000, v16
	v_add_f32_e32 v5, v5, v6
	v_lshlrev_b32_e32 v55, 16, v16
	v_mul_f32_e32 v6, v54, v54
	v_fmac_f32_e32 v6, v55, v55
	v_and_b32_e32 v56, 0xffff0000, v17
	v_add_f32_e32 v5, v6, v5
	v_lshlrev_b32_e32 v57, 16, v17
	v_mul_f32_e32 v6, v56, v56
	v_fmac_f32_e32 v6, v57, v57
	v_add_f32_e32 v5, v6, v5
	v_and_b32_e32 v48, 0xffff0000, v18
	v_and_b32_e32 v46, 0xffff0000, v19
	v_add_f32_e32 v4, v4, v5
	v_lshlrev_b32_e32 v49, 16, v18
	v_mul_f32_e32 v5, v48, v48
	v_lshlrev_b32_e32 v47, 16, v19
	v_mul_f32_e32 v6, v46, v46
	v_fmac_f32_e32 v5, v49, v49
	v_fmac_f32_e32 v6, v47, v47
	v_and_b32_e32 v44, 0xffff0000, v20
	v_add_f32_e32 v5, v5, v6
	v_lshlrev_b32_e32 v45, 16, v20
	v_mul_f32_e32 v6, v44, v44
	v_fmac_f32_e32 v6, v45, v45
	v_and_b32_e32 v42, 0xffff0000, v21
	v_add_f32_e32 v5, v6, v5
	v_lshlrev_b32_e32 v43, 16, v21
	v_mul_f32_e32 v6, v42, v42
	v_fmac_f32_e32 v6, v43, v43
	v_add_f32_e32 v5, v6, v5
	v_and_b32_e32 v40, 0xffff0000, v22
	v_and_b32_e32 v38, 0xffff0000, v23
	v_add_f32_e32 v4, v4, v5
	v_lshlrev_b32_e32 v41, 16, v22
	v_mul_f32_e32 v5, v40, v40
	v_lshlrev_b32_e32 v39, 16, v23
	v_mul_f32_e32 v6, v38, v38
	v_fmac_f32_e32 v5, v41, v41
	v_fmac_f32_e32 v6, v39, v39
	v_and_b32_e32 v36, 0xffff0000, v24
	v_add_f32_e32 v5, v5, v6
	v_lshlrev_b32_e32 v37, 16, v24
; __device__ __forceinline__ float bf_lo(unsigned u) { return __uint_as_float(u << 16); }
; __device__ __forceinline__ float bf_hi(unsigned u) { return __uint_as_float(u & 0xffff0000u); }
; __device__ __forceinline__ unsigned cvtpk(float lo, float hi) { unsigned r; asm volatile("v_cvt_pk_bf16_f32 %0, %1, %2" : "=v"(r) : "v"(lo), "v"(hi)); return r; }
; template <bool NATM, int QN> ...
;     ...
;     { auto rr = __builtin_amdgcn_permlane32_swap(__float_as_uint(ss), __float_as_uint(ss), false, false); ss = __uint_as_float(rr[0]) + __uint_as_float(rr[1]); }
;     const float rstd = QSCALE * __builtin_amdgcn_rsqf(ss * (1.0f / D) + NORM_EPS);
;     const int tok = qtok0 + wid * QBLK + r32, pr = tok >> 6, pc = tok & 63;
; #pragma unroll
;     for (int d0 = 0; d0 < 8; ++d0) { const u32x4 w = *reinterpret_cast<const u32x4*>(&qr[d0]);
;       const f32x4 g0 = *(const gf32x4*)(qg + d0 * 16 + hi * 8), g1 = *(const gf32x4*)(qg + d0 * 16 + hi * 8 + 4);
;       float y[8] = {bf_lo(w.x) * rstd * g0.x, bf_hi(w.x) * rstd * g0.y, bf_lo(w.y) * rstd * g0.z, bf_hi(w.y) * rstd * g0.w, bf_lo(w.z) * rstd * g1.x, bf_hi(w.z) * rstd * g1.y, bf_lo(w.w) * rstd * g1.z, bf_hi(w.w) * rstd * g1.w};
;       if constexpr (QN == 2) { const int pos = d0 < 4 ? pr : pc, f0 = (d0 & 3) * 8 + hi * 4;
;         const f32x4 t0 = *(const gf32x4*)(rope + 2 * (pos * 32 + f0)), t1 = *(const gf32x4*)(rope + 2 * (pos * 32 + f0) + 4);
;         const float a0 = y[0] * t0.x - y[1] * t0.y, b0 = y[0] * t0.y + y[1] * t0.x, a1 = y[2] * t0.z - y[3] * t0.w, b1 = y[2] * t0.w + y[3] * t0.z;
;         const float a2 = y[4] * t1.x - y[5] * t1.y, b2 = y[4] * t1.y + y[5] * t1.x, a3 = y[6] * t1.z - y[7] * t1.w, b3 = y[6] * t1.w + y[7] * t1.z;
;         y[0] = a0; y[1] = b0; y[2] = a1; y[3] = b1; y[4] = a2; y[5] = b2; y[6] = a3; y[7] = b3; }
;       u32x4 o4; o4.x = cvtpk(y[0], y[1]); o4.y = cvtpk(y[2], y[3]); o4.z = cvtpk(y[4], y[5]); o4.w = cvtpk(y[6], y[7]); qr[d0] = *reinterpret_cast<bf16x8*>(&o4); }
	v_mul_f32_e32 v6, v36, v36
	v_fmac_f32_e32 v6, v37, v37
	v_and_b32_e32 v34, 0xffff0000, v25
	v_add_f32_e32 v5, v6, v5
	v_lshlrev_b32_e32 v35, 16, v25
	v_mul_f32_e32 v6, v34, v34
	v_fmac_f32_e32 v6, v35, v35
	v_add_f32_e32 v5, v6, v5
	v_and_b32_e32 v32, 0xffff0000, v74
	v_and_b32_e32 v30, 0xffff0000, v75
	v_add_f32_e32 v4, v4, v5
	v_lshlrev_b32_e32 v33, 16, v74
	v_mul_f32_e32 v5, v32, v32
	v_lshlrev_b32_e32 v31, 16, v75
	v_mul_f32_e32 v6, v30, v30
	v_fmac_f32_e32 v5, v33, v33
	v_fmac_f32_e32 v6, v31, v31
	v_and_b32_e32 v28, 0xffff0000, v76
	v_add_f32_e32 v5, v5, v6
	v_lshlrev_b32_e32 v29, 16, v76
	v_mul_f32_e32 v6, v28, v28
	v_fmac_f32_e32 v6, v29, v29
	v_and_b32_e32 v26, 0xffff0000, v77
	v_add_f32_e32 v5, v6, v5
	v_lshlrev_b32_e32 v27, 16, v77
	v_mul_f32_e32 v6, v26, v26
	v_fmac_f32_e32 v6, v27, v27
	v_add_f32_e32 v5, v6, v5
	v_and_b32_e32 v24, 0xffff0000, v78
	v_and_b32_e32 v22, 0xffff0000, v79
	v_add_f32_e32 v4, v4, v5
	v_lshlrev_b32_e32 v25, 16, v78
	v_mul_f32_e32 v5, v24, v24
	v_lshlrev_b32_e32 v23, 16, v79
	v_mul_f32_e32 v6, v22, v22
	v_and_b32_e32 v9, 0xffff0000, v0
	v_and_b32_e32 v10, 0xffff0000, v1
	v_fmac_f32_e32 v5, v25, v25
	v_fmac_f32_e32 v6, v23, v23
	v_and_b32_e32 v20, 0xffff0000, v80
	v_lshlrev_b32_e32 v11, 16, v0
	v_mul_f32_e32 v0, v9, v9
	v_lshlrev_b32_e32 v12, 16, v1
	v_mul_f32_e32 v1, v10, v10
	v_add_f32_e32 v5, v5, v6
	v_lshlrev_b32_e32 v21, 16, v80
	v_mul_f32_e32 v6, v20, v20
	v_fmac_f32_e32 v0, v11, v11
	v_fmac_f32_e32 v1, v12, v12
	v_and_b32_e32 v13, 0xffff0000, v2
	v_fmac_f32_e32 v6, v21, v21
	v_and_b32_e32 v18, 0xffff0000, v81
	v_add_f32_e32 v0, v0, v1
	v_lshlrev_b32_e32 v14, 16, v2
	v_mul_f32_e32 v1, v13, v13
	v_add_f32_e32 v5, v6, v5
	v_lshlrev_b32_e32 v19, 16, v81
	v_mul_f32_e32 v6, v18, v18
	v_fmac_f32_e32 v1, v14, v14
	v_and_b32_e32 v15, 0xffff0000, v3
	v_fmac_f32_e32 v6, v19, v19
	v_add_f32_e32 v0, v1, v0
	v_lshlrev_b32_e32 v16, 16, v3
	v_mul_f32_e32 v1, v15, v15
	v_add_f32_e32 v5, v6, v5
	v_fmac_f32_e32 v1, v16, v16
	v_add_f32_e32 v4, v4, v5
	v_add_f32_e32 v0, v1, v0
	v_add_f32_e32 v0, v4, v0
	v_mov_b32_e32 v1, v0
	s_nop 1
	v_permlane32_swap_b32_e32 v0, v1
	v_add_f32_e32 v0, v0, v1
	v_fmamk_f32 v0, v0, 0x3c000000, v240
	v_rsq_f32_e32 v0, v0
	v_and_b32_e32 v74, 32, v167
	v_mul_f32_e32 v17, 0x3e0293ee, v0
	global_load_dwordx4 v[0:3], v74, s[36:37] offset:16
	global_load_dwordx4 v[4:7], v74, s[36:37]
	global_load_dwordx4 v[186:189], v74, s[36:37] offset:80
	global_load_dwordx4 v[190:193], v74, s[36:37] offset:64
	global_load_dwordx4 v[194:197], v74, s[36:37] offset:144
	global_load_dwordx4 v[198:201], v74, s[36:37] offset:128
	global_load_dwordx4 v[202:205], v74, s[36:37] offset:208
	global_load_dwordx4 v[206:209], v74, s[36:37] offset:192
	global_load_dwordx4 v[156:159], v74, s[36:37] offset:272
	global_load_dwordx4 v[162:165], v74, s[36:37] offset:256
	v_mul_f32_e32 v66, v17, v66
	v_mul_f32_e32 v67, v17, v67
	v_mul_f32_e32 v58, v17, v58
	v_mul_f32_e32 v59, v17, v59
	v_mul_f32_e32 v50, v17, v50
	v_mul_f32_e32 v51, v17, v51
	v_mul_f32_e32 v49, v17, v49
	v_mul_f32_e32 v48, v17, v48
	v_mul_f32_e32 v47, v17, v47
	v_mul_f32_e32 v46, v17, v46
	v_mul_f32_e32 v45, v17, v45
	v_mul_f32_e32 v44, v17, v44
	v_mul_f32_e32 v43, v17, v43
	v_mul_f32_e32 v42, v17, v42
	v_mul_f32_e32 v41, v17, v41
	v_mul_f32_e32 v40, v17, v40
	v_mul_f32_e32 v39, v17, v39
	v_mul_f32_e32 v38, v17, v38
	v_mul_f32_e32 v37, v17, v37
	v_mul_f32_e32 v36, v17, v36
	v_mul_f32_e32 v35, v17, v35
	v_mul_f32_e32 v34, v17, v34
	v_mul_f32_e32 v33, v17, v33
	v_mul_f32_e32 v32, v17, v32
	v_mul_f32_e32 v31, v17, v31
	v_mul_f32_e32 v30, v17, v30
	v_mul_f32_e32 v29, v17, v29
	v_mul_f32_e32 v28, v17, v28
	v_mul_f32_e32 v27, v17, v27
	v_mul_f32_e32 v26, v17, v26
	v_mul_f32_e32 v25, v17, v25
	v_mul_f32_e32 v24, v17, v24
	v_mul_f32_e32 v23, v17, v23
	v_mul_f32_e32 v22, v17, v22
	v_mul_f32_e32 v21, v17, v21
	v_mul_f32_e32 v20, v17, v20
	v_mul_f32_e32 v19, v17, v19
	v_mul_f32_e32 v18, v17, v18
	v_mul_f32_e32 v9, v17, v9
	v_mul_f32_e32 v11, v17, v11
	s_waitcnt vmcnt(8)
	v_mul_f32_e32 v5, v5, v66
	v_mul_f32_e32 v66, v17, v69
	v_mul_f32_e32 v6, v6, v66
	v_mul_f32_e32 v66, v17, v68
	v_mul_f32_e32 v7, v7, v66
	v_mul_f32_e32 v66, v17, v71
	v_mul_f32_e32 v0, v0, v66
	v_mul_f32_e32 v66, v17, v70
	v_mul_f32_e32 v1, v1, v66
	v_mul_f32_e32 v66, v17, v73
	v_mul_f32_e32 v2, v2, v66
	v_mul_f32_e32 v66, v17, v72
	v_mul_f32_e32 v4, v4, v67
	v_mul_f32_e32 v3, v3, v66
	v_cvt_pk_bf16_f32 v112, v4, v5
	v_cvt_pk_bf16_f32 v113, v6, v7
	v_cvt_pk_bf16_f32 v114, v0, v1
	v_cvt_pk_bf16_f32 v115, v2, v3
	global_load_dwordx4 v[0:3], v74, s[36:37] offset:336
	global_load_dwordx4 v[4:7], v74, s[36:37] offset:320
	s_waitcnt vmcnt(8)
	v_mul_f32_e32 v191, v191, v58
	v_mul_f32_e32 v58, v17, v61
	v_mul_f32_e32 v192, v192, v58
	v_mul_f32_e32 v58, v17, v60
	v_mul_f32_e32 v193, v193, v58
	v_mul_f32_e32 v58, v17, v63
	v_mul_f32_e32 v186, v58, v186
	v_mul_f32_e32 v58, v17, v62
	v_mul_f32_e32 v187, v58, v187
	v_mul_f32_e32 v58, v17, v65
	v_mul_f32_e32 v188, v58, v188
	v_mul_f32_e32 v58, v17, v64
	v_mul_f32_e32 v190, v190, v59
	v_mul_f32_e32 v189, v58, v189
	v_cvt_pk_bf16_f32 v116, v190, v191
	v_cvt_pk_bf16_f32 v117, v192, v193
	v_cvt_pk_bf16_f32 v118, v186, v187
	v_cvt_pk_bf16_f32 v119, v188, v189
	global_load_dwordx4 v[186:189], v74, s[36:37] offset:400
	global_load_dwordx4 v[190:193], v74, s[36:37] offset:384
	s_waitcnt vmcnt(8)
; __device__ __forceinline__ float bf_lo(unsigned u) { return __uint_as_float(u << 16); }
; __device__ __forceinline__ float bf_hi(unsigned u) { return __uint_as_float(u & 0xffff0000u); }
; __device__ __forceinline__ unsigned cvtpk(float lo, float hi) { unsigned r; asm volatile("v_cvt_pk_bf16_f32 %0, %1, %2" : "=v"(r) : "v"(lo), "v"(hi)); return r; }
; __device__ __forceinline__ void qkt(f32x16& p0, f32x16& p1, const char* Ks, const bf16x8* qr, int r32, int hi, float negm) {
; #pragma unroll
;   for (int r = 0; r < 16; ++r) { p0[r] = negm; p1[r] = negm; }
; #pragma unroll
;   for (int d0 = 0; d0 < 8; ++d0) { int cb = (d0 * 16 + hi * 8) * 2;
;     bf16x8 b0 = *reinterpret_cast<const bf16x8*>(Ks + KSWZ(r32, cb));
;     bf16x8 b1 = *reinterpret_cast<const bf16x8*>(Ks + KSWZ(32 + r32, cb));
;     p0 = __builtin_amdgcn_mfma_f32_32x32x16_bf16(b0, qr[d0], p0, 0, 0, 0);
;     p1 = __builtin_amdgcn_mfma_f32_32x32x16_bf16(b1, qr[d0], p1, 0, 0, 0); }
; template <bool NATM, int QN> ...
;     ...
;     for (int d0 = 0; d0 < 8; ++d0) { const u32x4 w = *reinterpret_cast<const u32x4*>(&qr[d0]);
;       const f32x4 g0 = *(const gf32x4*)(qg + d0 * 16 + hi * 8), g1 = *(const gf32x4*)(qg + d0 * 16 + hi * 8 + 4);
;       float y[8] = {bf_lo(w.x) * rstd * g0.x, bf_hi(w.x) * rstd * g0.y, bf_lo(w.y) * rstd * g0.z, bf_hi(w.y) * rstd * g0.w, bf_lo(w.z) * rstd * g1.x, bf_hi(w.z) * rstd * g1.y, bf_lo(w.w) * rstd * g1.z, bf_hi(w.w) * rstd * g1.w};
;       if constexpr (QN == 2) { const int pos = d0 < 4 ? pr : pc, f0 = (d0 & 3) * 8 + hi * 4;
;         const f32x4 t0 = *(const gf32x4*)(rope + 2 * (pos * 32 + f0)), t1 = *(const gf32x4*)(rope + 2 * (pos * 32 + f0) + 4);
;         const float a0 = y[0] * t0.x - y[1] * t0.y, b0 = y[0] * t0.y + y[1] * t0.x, a1 = y[2] * t0.z - y[3] * t0.w, b1 = y[2] * t0.w + y[3] * t0.z;
;         const float a2 = y[4] * t1.x - y[5] * t1.y, b2 = y[4] * t1.y + y[5] * t1.x, a3 = y[6] * t1.z - y[7] * t1.w, b3 = y[6] * t1.w + y[7] * t1.z;
;         y[0] = a0; y[1] = b0; y[2] = a1; y[3] = b1; y[4] = a2; y[5] = b2; y[6] = a3; y[7] = b3; }
;       u32x4 o4; o4.x = cvtpk(y[0], y[1]); o4.y = cvtpk(y[2], y[3]); o4.z = cvtpk(y[4], y[5]); o4.w = cvtpk(y[6], y[7]); qr[d0] = *reinterpret_cast<bf16x8*>(&o4); }
;     ...
;   LANDED();
;   qkt(pA0, pA1, K_lds, qr, r32, hi, 0.f); NMASK(pA0, pA1, 0); partialSM<true>(pA0, pA1, m_reg, alA);
	v_mul_f32_e32 v199, v50, v199
	v_mul_f32_e32 v50, v17, v53
	v_mul_f32_e32 v200, v50, v200
	v_mul_f32_e32 v50, v17, v52
	v_mul_f32_e32 v201, v50, v201
	v_mul_f32_e32 v50, v17, v55
	v_mul_f32_e32 v194, v50, v194
	v_mul_f32_e32 v50, v17, v54
	v_mul_f32_e32 v195, v50, v195
	v_mul_f32_e32 v50, v17, v57
	v_mul_f32_e32 v196, v50, v196
	v_mul_f32_e32 v50, v17, v56
	v_mul_f32_e32 v198, v51, v198
	v_mul_f32_e32 v197, v50, v197
	v_cvt_pk_bf16_f32 v120, v198, v199
	v_cvt_pk_bf16_f32 v121, v200, v201
	v_cvt_pk_bf16_f32 v122, v194, v195
	v_cvt_pk_bf16_f32 v123, v196, v197
	global_load_dwordx4 v[194:197], v74, s[36:37] offset:464
	global_load_dwordx4 v[198:201], v74, s[36:37] offset:448
	s_waitcnt vmcnt(8)
	v_mul_f32_e32 v202, v45, v202
	v_mul_f32_e32 v206, v49, v206
	v_mul_f32_e32 v207, v48, v207
	v_mul_f32_e32 v208, v47, v208
	v_mul_f32_e32 v209, v46, v209
	v_mul_f32_e32 v203, v44, v203
	v_mul_f32_e32 v204, v43, v204
	v_mul_f32_e32 v205, v42, v205
	v_cvt_pk_bf16_f32 v124, v206, v207
	v_cvt_pk_bf16_f32 v125, v208, v209
	v_cvt_pk_bf16_f32 v126, v202, v203
	v_cvt_pk_bf16_f32 v127, v204, v205
	s_waitcnt vmcnt(6)
	v_mul_f32_e32 v156, v37, v156
	v_mul_f32_e32 v162, v41, v162
	v_mul_f32_e32 v163, v40, v163
	v_mul_f32_e32 v164, v39, v164
	v_mul_f32_e32 v165, v38, v165
	v_mul_f32_e32 v157, v36, v157
	v_mul_f32_e32 v158, v35, v158
	v_mul_f32_e32 v159, v34, v159
	v_cvt_pk_bf16_f32 v128, v162, v163
	v_cvt_pk_bf16_f32 v129, v164, v165
	v_cvt_pk_bf16_f32 v130, v156, v157
	v_cvt_pk_bf16_f32 v131, v158, v159
	v_lshlrev_b32_e32 v40, 8, v151
	v_and_b32_e32 v41, 0x70, v8
	s_waitcnt vmcnt(4)
	v_mul_f32_e32 v0, v29, v0
	v_mul_f32_e32 v4, v33, v4
	v_mul_f32_e32 v5, v32, v5
	v_mul_f32_e32 v6, v31, v6
	v_mul_f32_e32 v7, v30, v7
	v_mul_f32_e32 v1, v28, v1
	v_mul_f32_e32 v2, v27, v2
	v_mul_f32_e32 v3, v26, v3
	v_cvt_pk_bf16_f32 v132, v4, v5
	v_cvt_pk_bf16_f32 v133, v6, v7
	v_cvt_pk_bf16_f32 v134, v0, v1
	v_cvt_pk_bf16_f32 v135, v2, v3
	v_or_b32_e32 v32, 32, v144
	v_bitop3_b32 v32, v32, v40, v41 bitop3:0xde
	v_add_u32_e32 v154, 0, v32
	s_waitcnt vmcnt(2)
	v_mul_f32_e32 v186, v21, v186
	v_mul_f32_e32 v190, v25, v190
	v_mul_f32_e32 v191, v24, v191
	v_mul_f32_e32 v192, v23, v192
	v_mul_f32_e32 v193, v22, v193
	v_mul_f32_e32 v187, v20, v187
	v_mul_f32_e32 v188, v19, v188
	v_mul_f32_e32 v189, v18, v189
	v_cvt_pk_bf16_f32 v136, v190, v191
	v_cvt_pk_bf16_f32 v137, v192, v193
	v_cvt_pk_bf16_f32 v138, v186, v187
	v_cvt_pk_bf16_f32 v139, v188, v189
	s_waitcnt vmcnt(0)
	v_mul_f32_e32 v199, v9, v199
	v_mul_f32_e32 v9, v17, v12
	v_mul_f32_e32 v200, v9, v200
	v_mul_f32_e32 v9, v17, v10
	v_mul_f32_e32 v201, v9, v201
	v_mul_f32_e32 v9, v17, v14
	v_mul_f32_e32 v194, v9, v194
	v_mul_f32_e32 v9, v17, v13
	v_mul_f32_e32 v195, v9, v195
	v_mul_f32_e32 v9, v17, v16
	v_mul_f32_e32 v196, v9, v196
	v_mul_f32_e32 v9, v17, v15
	v_mul_f32_e32 v198, v11, v198
	v_mul_f32_e32 v197, v9, v197
	v_cvt_pk_bf16_f32 v140, v198, v199
	v_cvt_pk_bf16_f32 v141, v200, v201
	v_cvt_pk_bf16_f32 v142, v194, v195
	v_cvt_pk_bf16_f32 v143, v196, v197
	v_lshlrev_b32_e32 v0, 3, v97
	v_and_b32_e32 v1, 0xc0, v8
	v_lshlrev_b32_e32 v2, 1, v167
	v_and_or_b32 v1, v0, 24, v1
	v_and_b32_e32 v2, 32, v2
	v_and_b32_e32 v0, 0x100, v0
	v_or3_b32 v98, v1, v2, v0
	v_bitop3_b32 v0, v144, v40, v41 bitop3:0xde
	v_add_u32_e32 v152, 0, v0
	s_waitcnt vmcnt(0)
	s_waitcnt lgkmcnt(0)
	s_barrier
	ds_read_b128 v[0:3], v152 offset:32768
	ds_read_b128 v[16:19], v152 offset:40960
	s_waitcnt lgkmcnt(1)
	v_mfma_f32_32x32x16_bf16 v[0:15], v[0:3], v[112:115], 0
	ds_read_b128 v[32:35], v154 offset:32768
	ds_read_b128 v[36:39], v154 offset:40960
	v_add_u32_e32 v145, s6, v98
	s_add_u32 s6, s4, 0x20000
	s_addc_u32 s7, s5, 0
	s_add_u32 s2, s0, 0x10000
	s_waitcnt lgkmcnt(2)
	v_mfma_f32_32x32x16_bf16 v[16:31], v[16:19], v[112:115], 0
	s_waitcnt lgkmcnt(1)
	v_mfma_f32_32x32x16_bf16 v[0:15], v[32:35], v[116:119], v[0:15]
	v_or_b32_e32 v32, 64, v144
	v_bitop3_b32 v32, v32, v40, v41 bitop3:0xde
	v_add_u32_e32 v156, 0, v32
	s_waitcnt lgkmcnt(0)
	v_mfma_f32_32x32x16_bf16 v[16:31], v[36:39], v[116:119], v[16:31]
	ds_read_b128 v[32:35], v156 offset:32768
	ds_read_b128 v[36:39], v156 offset:40960
	s_waitcnt lgkmcnt(1)
	v_mfma_f32_32x32x16_bf16 v[0:15], v[32:35], v[120:123], v[0:15]
	v_or_b32_e32 v32, 0x60, v144
	v_bitop3_b32 v32, v32, v40, v41 bitop3:0xde
	v_add_u32_e32 v157, 0, v32
	s_waitcnt lgkmcnt(0)
	v_mfma_f32_32x32x16_bf16 v[16:31], v[36:39], v[120:123], v[16:31]
	ds_read_b128 v[32:35], v157 offset:32768
	ds_read_b128 v[36:39], v157 offset:40960
	s_waitcnt lgkmcnt(1)
	v_mfma_f32_32x32x16_bf16 v[0:15], v[32:35], v[124:127], v[0:15]
	v_or_b32_e32 v32, 0x80, v144
	v_bitop3_b32 v32, v32, v40, v41 bitop3:0xde
	v_add_u32_e32 v158, 0, v32
	s_waitcnt lgkmcnt(0)
	v_mfma_f32_32x32x16_bf16 v[16:31], v[36:39], v[124:127], v[16:31]
	ds_read_b128 v[32:35], v158 offset:32768
	ds_read_b128 v[36:39], v158 offset:40960
	s_waitcnt lgkmcnt(1)
	v_mfma_f32_32x32x16_bf16 v[0:15], v[32:35], v[128:131], v[0:15]
	v_or_b32_e32 v32, 0xa0, v144
	v_bitop3_b32 v32, v32, v40, v41 bitop3:0xde
	v_add_u32_e32 v159, 0, v32
	s_waitcnt lgkmcnt(0)
	v_mfma_f32_32x32x16_bf16 v[16:31], v[36:39], v[128:131], v[16:31]
	ds_read_b128 v[32:35], v159 offset:32768
	ds_read_b128 v[36:39], v159 offset:40960
	s_waitcnt lgkmcnt(1)
	v_mfma_f32_32x32x16_bf16 v[0:15], v[32:35], v[132:135], v[0:15]
	v_or_b32_e32 v32, 0xc0, v144
	v_bitop3_b32 v32, v32, v40, v41 bitop3:0xde
	v_add_u32_e32 v162, 0, v32
	s_waitcnt lgkmcnt(0)
	v_mfma_f32_32x32x16_bf16 v[16:31], v[36:39], v[132:135], v[16:31]
	ds_read_b128 v[32:35], v162 offset:32768
	ds_read_b128 v[36:39], v162 offset:40960
	s_waitcnt lgkmcnt(1)
	v_mfma_f32_32x32x16_bf16 v[0:15], v[32:35], v[136:139], v[0:15]
	v_or_b32_e32 v32, 0xe0, v144
	v_bitop3_b32 v32, v32, v40, v41 bitop3:0xde
	v_add_u32_e32 v163, 0, v32
	s_waitcnt lgkmcnt(0)
	v_mfma_f32_32x32x16_bf16 v[16:31], v[36:39], v[136:139], v[16:31]
	ds_read_b128 v[32:35], v163 offset:32768
	ds_read_b128 v[36:39], v163 offset:40960
	s_waitcnt lgkmcnt(0)
	s_barrier
; template <bool FIRST>
; __device__ __forceinline__ void partialSM(f32x16& p0, f32x16& p1, float& m_reg, float& alpha) {
;   constexpr float THRL = THR * 1.4426950408889634f;
;   float pmax = p0[0];
; #pragma unroll
;   for (int r = 1; r < 16; ++r) pmax = fmaxf(pmax, p0[r]);
; #pragma unroll
;   for (int r = 0; r < 16; ++r) pmax = fmaxf(pmax, p1[r]);
;   { auto rr = __builtin_amdgcn_permlane32_swap(__float_as_uint(pmax), __float_as_uint(pmax), false, false);
;     pmax = fmaxf(__uint_as_float(rr[0]), __uint_as_float(rr[1])); }
;   if (!FIRST && __builtin_expect(__all(pmax <= THRL), 1)) { alpha = 1.f; }
;   else { const float delta = FIRST ? pmax : fmaxf(pmax, 0.f); alpha = FIRST ? 1.f : __builtin_amdgcn_exp2f(-delta); m_reg += delta;
; #pragma unroll
;     for (int r = 0; r < 16; ++r) { p0[r] -= delta; p1[r] -= delta; } }
; #pragma unroll
;   for (int r = 0; r < 16; ++r) p0[r] = __builtin_amdgcn_exp2f(p0[r]);
; }
; __device__ __forceinline__ void finishSM(f32x16& p0, f32x16& p1, float alpha, float& l_reg, bf16x8& pa0, bf16x8& pa1, bf16x8& pa2, bf16x8& pa3) {
; #pragma unroll
;   for (int r = 0; r < 16; ++r) p1[r] = __builtin_amdgcn_exp2f(p1[r]);
;   float ps = 0;
; #pragma unroll
;   for (int r = 0; r < 16; ++r) ps += p0[r];
; #pragma unroll
;   for (int r = 0; r < 16; ++r) ps += p1[r];
;   { auto rr = __builtin_amdgcn_permlane32_swap(__float_as_uint(ps), __float_as_uint(ps), false, false);
;     ps = __uint_as_float(rr[0]) + __uint_as_float(rr[1]); }
;   l_reg = l_reg * alpha + ps;
;     ...
;   PK4(p0, 0, pa0); PK4(p0, 8, pa1); PK4(p1, 0, pa2); PK4(p1, 8, pa3);
;     ...
; }
; __device__ __forceinline__ void qkt(f32x16& p0, f32x16& p1, const char* Ks, const bf16x8* qr, int r32, int hi, float negm) {
; #pragma unroll
;   for (int r = 0; r < 16; ++r) { p0[r] = negm; p1[r] = negm; }
; #pragma unroll
;   for (int d0 = 0; d0 < 8; ++d0) { int cb = (d0 * 16 + hi * 8) * 2;
;     bf16x8 b0 = *reinterpret_cast<const bf16x8*>(Ks + KSWZ(r32, cb));
;     bf16x8 b1 = *reinterpret_cast<const bf16x8*>(Ks + KSWZ(32 + r32, cb));
;     p0 = __builtin_amdgcn_mfma_f32_32x32x16_bf16(b0, qr[d0], p0, 0, 0, 0);
;     p1 = __builtin_amdgcn_mfma_f32_32x32x16_bf16(b1, qr[d0], p1, 0, 0, 0); }
; template <bool NATM, int QN> ...
;     ...
;     KDMA(0, KROW(j + 1)); VDMA(1, KROW(j));
	global_load_lds_dwordx4 v160, s[6:7]
	s_mov_b32 m0, s3
	s_addc_u32 s3, s1, 0
	s_add_i32 s53, s19, 0x4000
	global_load_lds_dwordx4 v96, s[6:7]
	s_mov_b32 m0, s53
	s_add_i32 s7, s19, 0x6000
	global_load_lds_dwordx4 v146, s[2:3]
	s_mov_b32 m0, s7
	v_mfma_f32_32x32x16_bf16 v[0:15], v[32:35], v[140:143], v[0:15]
	global_load_lds_dwordx4 v148, s[2:3]
	v_mfma_f32_32x32x16_bf16 v[16:31], v[36:39], v[140:143], v[16:31]
	s_nop 9
	v_max_f32_e32 v32, v1, v1
	v_max_f32_e32 v33, v0, v0
	v_max_f32_e32 v32, v33, v32
	v_max3_f32 v32, v32, v2, v3
	v_max3_f32 v32, v32, v4, v5
	v_max3_f32 v32, v32, v6, v7
	v_max3_f32 v32, v32, v8, v9
	v_max3_f32 v32, v32, v10, v11
	v_max3_f32 v32, v32, v12, v13
	v_max3_f32 v32, v32, v14, v15
	v_max3_f32 v32, v32, v16, v17
	v_max3_f32 v32, v32, v18, v19
	v_max3_f32 v32, v32, v20, v21
	v_max3_f32 v32, v32, v22, v23
	v_max3_f32 v32, v32, v24, v25
	v_max3_f32 v32, v32, v26, v27
	v_max3_f32 v32, v32, v28, v29
	v_max3_f32 v32, v32, v30, v31
	v_mov_b32_e32 v33, v32
	s_nop 1
	v_permlane32_swap_b32_e32 v32, v33
	v_max_f32_e32 v33, v33, v33
	v_max_f32_e32 v32, v32, v32
	v_max_f32_e32 v35, v32, v33
	v_sub_f32_e32 v0, v0, v35
	v_sub_f32_e32 v1, v1, v35
	v_sub_f32_e32 v2, v2, v35
	v_sub_f32_e32 v3, v3, v35
	v_sub_f32_e32 v32, v19, v35
	v_sub_f32_e32 v4, v4, v35
	v_sub_f32_e32 v33, v20, v35
	v_sub_f32_e32 v5, v5, v35
	v_sub_f32_e32 v6, v6, v35
	v_sub_f32_e32 v19, v22, v35
	v_sub_f32_e32 v7, v7, v35
	v_sub_f32_e32 v20, v23, v35
	v_sub_f32_e32 v36, v8, v35
	v_sub_f32_e32 v37, v9, v35
	v_sub_f32_e32 v22, v25, v35
	v_sub_f32_e32 v38, v10, v35
	v_sub_f32_e32 v39, v11, v35
	v_sub_f32_e32 v40, v12, v35
	v_sub_f32_e32 v41, v13, v35
	v_sub_f32_e32 v23, v29, v35
	v_sub_f32_e32 v29, v14, v35
	v_sub_f32_e32 v25, v30, v35
	v_sub_f32_e32 v30, v15, v35
	v_exp_f32_e32 v8, v0
	v_exp_f32_e32 v9, v1
	v_exp_f32_e32 v10, v2
	v_exp_f32_e32 v11, v3
	v_exp_f32_e32 v12, v4
	v_exp_f32_e32 v13, v5
	v_exp_f32_e32 v14, v6
	v_exp_f32_e32 v15, v7
	v_exp_f32_e32 v0, v36
	v_exp_f32_e32 v1, v37
	v_exp_f32_e32 v2, v38
	v_exp_f32_e32 v3, v39
	v_exp_f32_e32 v4, v40
	v_exp_f32_e32 v5, v41
	v_exp_f32_e32 v6, v29
	v_exp_f32_e32 v7, v30
	v_add_f32_e32 v164, 0, v35
	v_sub_f32_e32 v16, v16, v35
	v_sub_f32_e32 v17, v17, v35
	v_sub_f32_e32 v18, v18, v35
	v_sub_f32_e32 v34, v21, v35
	v_sub_f32_e32 v21, v24, v35
	v_sub_f32_e32 v24, v26, v35
	v_sub_f32_e32 v26, v27, v35
	v_sub_f32_e32 v28, v28, v35
	v_sub_f32_e32 v27, v31, v35
	ds_read_b128 v[36:39], v152 offset:49152
	ds_read_b128 v[40:43], v152 offset:57344
	v_xor_b32_e32 v64, 0x80000000, v164
	v_mov_b32_e32 v65, v64
	v_mov_b32_e32 v66, v64
	v_mov_b32_e32 v67, v64
	v_mov_b32_e32 v68, v64
	v_mov_b32_e32 v69, v64
	v_mov_b32_e32 v70, v64
	v_mov_b32_e32 v71, v64
	v_mov_b32_e32 v72, v64
	v_mov_b32_e32 v73, v64
	v_mov_b32_e32 v74, v64
	v_mov_b32_e32 v75, v64
	v_mov_b32_e32 v76, v64
	v_mov_b32_e32 v77, v64
	v_mov_b32_e32 v78, v64
	v_mov_b32_e32 v79, v64
	v_exp_f32_e32 v29, v32
	v_add_f32_e32 v32, 0, v8
	s_waitcnt lgkmcnt(0)
	v_mfma_f32_32x32x16_bf16 v[80:95], v[36:39], v[112:115], v[64:79]
	v_add_f32_e32 v32, v9, v32
	v_add_f32_e32 v32, v10, v32
	v_add_f32_e32 v32, v11, v32
	v_add_f32_e32 v32, v12, v32
	v_add_f32_e32 v32, v13, v32
	v_add_f32_e32 v32, v14, v32
	v_add_f32_e32 v32, v15, v32
	v_mfma_f32_32x32x16_bf16 v[64:79], v[40:43], v[112:115], v[64:79]
	ds_read_b128 v[36:39], v154 offset:49152
	ds_read_b128 v[40:43], v154 offset:57344
	v_add_f32_e32 v32, v0, v32
	v_add_f32_e32 v32, v1, v32
	v_add_f32_e32 v32, v2, v32
	v_add_f32_e32 v32, v3, v32
	v_exp_f32_e32 v16, v16
	v_add_f32_e32 v32, v4, v32
	s_waitcnt lgkmcnt(0)
	v_mfma_f32_32x32x16_bf16 v[80:95], v[36:39], v[116:119], v[80:95]
	v_exp_f32_e32 v17, v17
	v_add_f32_e32 v32, v5, v32
	v_exp_f32_e32 v18, v18
	v_add_f32_e32 v32, v6, v32
	v_add_f32_e32 v32, v7, v32
	v_exp_f32_e32 v30, v33
	v_add_f32_e32 v32, v16, v32
	v_mfma_f32_32x32x16_bf16 v[64:79], v[40:43], v[116:119], v[64:79]
	ds_read_b128 v[36:39], v156 offset:49152
	ds_read_b128 v[40:43], v156 offset:57344
	v_exp_f32_e32 v31, v34
	v_add_f32_e32 v32, v17, v32
	v_exp_f32_e32 v19, v19
	v_add_f32_e32 v32, v18, v32
	v_exp_f32_e32 v20, v20
	v_add_f32_e32 v32, v29, v32
	s_waitcnt lgkmcnt(0)
	v_mfma_f32_32x32x16_bf16 v[80:95], v[36:39], v[120:123], v[80:95]
	v_exp_f32_e32 v21, v21
	v_add_f32_e32 v32, v30, v32
	v_exp_f32_e32 v22, v22
	v_add_f32_e32 v32, v31, v32
	v_exp_f32_e32 v24, v24
	v_add_f32_e32 v32, v19, v32
	v_exp_f32_e32 v26, v26
	v_mfma_f32_32x32x16_bf16 v[64:79], v[40:43], v[120:123], v[64:79]
	ds_read_b128 v[36:39], v157 offset:49152
	ds_read_b128 v[40:43], v157 offset:57344
	v_add_f32_e32 v32, v20, v32
	v_exp_f32_e32 v28, v28
	v_add_f32_e32 v32, v21, v32
	v_exp_f32_e32 v23, v23
	v_add_f32_e32 v32, v22, v32
	v_exp_f32_e32 v25, v25
	s_waitcnt lgkmcnt(0)
	v_mfma_f32_32x32x16_bf16 v[80:95], v[36:39], v[124:127], v[80:95]
	v_add_f32_e32 v32, v24, v32
	v_exp_f32_e32 v27, v27
	v_add_f32_e32 v32, v26, v32
	v_add_f32_e32 v32, v28, v32
	v_add_f32_e32 v32, v23, v32
	v_add_f32_e32 v32, v25, v32
	v_add_f32_e32 v153, v27, v32
	v_mfma_f32_32x32x16_bf16 v[64:79], v[40:43], v[124:127], v[64:79]
	ds_read_b128 v[36:39], v158 offset:49152
	ds_read_b128 v[40:43], v158 offset:57344
	v_mov_b32_e32 v155, v153
	s_nop 1
	v_permlane32_swap_b32_e32 v153, v155
	s_waitcnt lgkmcnt(0)
; #define SBAR() __builtin_amdgcn_sched_barrier(0)
; __device__ __forceinline__ void finishSM(f32x16& p0, f32x16& p1, float alpha, float& l_reg, bf16x8& pa0, bf16x8& pa1, bf16x8& pa2, bf16x8& pa3) {
; #pragma unroll
;   for (int r = 0; r < 16; ++r) p1[r] = __builtin_amdgcn_exp2f(p1[r]);
;   float ps = 0;
; #pragma unroll
;   for (int r = 0; r < 16; ++r) ps += p0[r];
; #pragma unroll
;   for (int r = 0; r < 16; ++r) ps += p1[r];
;   { auto rr = __builtin_amdgcn_permlane32_swap(__float_as_uint(ps), __float_as_uint(ps), false, false);
;     ps = __uint_as_float(rr[0]) + __uint_as_float(rr[1]); }
;   l_reg = l_reg * alpha + ps;
;     ...
;   PK4(p0, 0, pa0); PK4(p0, 8, pa1); PK4(p1, 0, pa2); PK4(p1, 8, pa3);
;     ...
; }
; __device__ __forceinline__ void qkt(f32x16& p0, f32x16& p1, const char* Ks, const bf16x8* qr, int r32, int hi, float negm) {
; #pragma unroll
;   for (int r = 0; r < 16; ++r) { p0[r] = negm; p1[r] = negm; }
; #pragma unroll
;   for (int d0 = 0; d0 < 8; ++d0) { int cb = (d0 * 16 + hi * 8) * 2;
;     bf16x8 b0 = *reinterpret_cast<const bf16x8*>(Ks + KSWZ(r32, cb));
;     bf16x8 b1 = *reinterpret_cast<const bf16x8*>(Ks + KSWZ(32 + r32, cb));
;     p0 = __builtin_amdgcn_mfma_f32_32x32x16_bf16(b0, qr[d0], p0, 0, 0, 0);
;     p1 = __builtin_amdgcn_mfma_f32_32x32x16_bf16(b1, qr[d0], p1, 0, 0, 0); }
; }
; __device__ __forceinline__ int v_st(int k, int c) { const int kk = (k & ~0xC) | ((k & 4) << 1) | ((k & 8) >> 1); return ((kk >> 3) * 4 + (c >> 5)) * 512 + ((kk & 7) * 32 + (c & 31)) * 2; }
; __device__ __forceinline__ int v_rd_base(int lane) { return ((lane & 3) << 3) | (((lane >> 2) & 3) << 6) | (((lane >> 4) & 1) << 5) | (((lane >> 5) & 1) << 8); }
; template <int OFF> __device__ __forceinline__ s16x4 tr_read(int vb) {
;   s16x4 r; asm volatile("ds_read_b64_tr_b16 %0, %1 offset:%2" : "=&v"(r) : "v"(vb), "i"(OFF) : "memory"); return r;
; }
; template <int D0> __device__ __forceinline__ void pv_one(f32x16& od, int vb, bf16x8 pa0, bf16x8 pa1, bf16x8 pa2, bf16x8 pa3) {
;   const s16x4 l0 = tr_read<v_rd_off(D0, 0, 0)>(vb), h0 = tr_read<v_rd_off(D0, 0, 1)>(vb), l1 = tr_read<v_rd_off(D0, 1, 0)>(vb), h1 = tr_read<v_rd_off(D0, 1, 1)>(vb);
;   const s16x4 l2 = tr_read<v_rd_off(D0, 2, 0)>(vb), h2 = tr_read<v_rd_off(D0, 2, 1)>(vb), l3 = tr_read<v_rd_off(D0, 3, 0)>(vb), h3 = tr_read<v_rd_off(D0, 3, 1)>(vb);
;   asm volatile("s_waitcnt lgkmcnt(0)" ::: "memory"); SBAR();
	v_mfma_f32_32x32x16_bf16 v[80:95], v[36:39], v[128:131], v[80:95]
	v_mfma_f32_32x32x16_bf16 v[64:79], v[40:43], v[128:131], v[64:79]
	ds_read_b128 v[36:39], v159 offset:49152
	ds_read_b128 v[40:43], v159 offset:57344
	s_waitcnt lgkmcnt(0)
	v_mfma_f32_32x32x16_bf16 v[80:95], v[36:39], v[132:135], v[80:95]
	v_mfma_f32_32x32x16_bf16 v[64:79], v[40:43], v[132:135], v[64:79]
	ds_read_b128 v[36:39], v162 offset:49152
	ds_read_b128 v[40:43], v162 offset:57344
	s_waitcnt lgkmcnt(0)
	v_mfma_f32_32x32x16_bf16 v[80:95], v[36:39], v[136:139], v[80:95]
	v_mfma_f32_32x32x16_bf16 v[64:79], v[40:43], v[136:139], v[64:79]
	ds_read_b128 v[36:39], v163 offset:49152
	ds_read_b128 v[40:43], v163 offset:57344
	v_cvt_pk_bf16_f32 v48, v8, v9
	v_cvt_pk_bf16_f32 v49, v10, v11
	v_cvt_pk_bf16_f32 v50, v12, v13
	v_cvt_pk_bf16_f32 v51, v14, v15
	v_cvt_pk_bf16_f32 v100, v0, v1
	v_cvt_pk_bf16_f32 v101, v2, v3
	s_waitcnt lgkmcnt(0)
	v_mfma_f32_32x32x16_bf16 v[80:95], v[36:39], v[140:143], v[80:95]
	v_permlane32_swap_b32_e32 v48, v50
	v_permlane32_swap_b32_e32 v49, v51
	v_cvt_pk_bf16_f32 v102, v4, v5
	v_cvt_pk_bf16_f32 v103, v6, v7
	v_cvt_pk_bf16_f32 v104, v16, v17
	v_mfma_f32_32x32x16_bf16 v[64:79], v[40:43], v[140:143], v[64:79]
	v_cvt_pk_bf16_f32 v105, v18, v29
	v_cvt_pk_bf16_f32 v106, v30, v31
	v_cvt_pk_bf16_f32 v107, v19, v20
	v_cvt_pk_bf16_f32 v108, v21, v22
	v_cvt_pk_bf16_f32 v109, v24, v26
	v_cvt_pk_bf16_f32 v110, v28, v23
	v_cvt_pk_bf16_f32 v111, v25, v27
	v_permlane32_swap_b32_e32 v100, v102
	v_permlane32_swap_b32_e32 v101, v103
	v_permlane32_swap_b32_e32 v104, v106
	v_permlane32_swap_b32_e32 v105, v107
	v_permlane32_swap_b32_e32 v108, v110
	v_permlane32_swap_b32_e32 v109, v111
	ds_read_b64_tr_b16 v[0:1], v145 offset:0
	ds_read_b64_tr_b16 v[2:3], v145 offset:0x800
	ds_read_b64_tr_b16 v[16:17], v145 offset:0x1000
	ds_read_b64_tr_b16 v[18:19], v145 offset:0x1800
	ds_read_b64_tr_b16 v[20:21], v145 offset:0x2000
	ds_read_b64_tr_b16 v[22:23], v145 offset:0x2800
	ds_read_b64_tr_b16 v[24:25], v145 offset:0x3000
	ds_read_b64_tr_b16 v[26:27], v145 offset:0x3800
	s_waitcnt lgkmcnt(0)
	s_nop 0
	v_mfma_f32_32x32x16_bf16 v[0:15], v[48:51], v[0:3], 0
	v_mfma_f32_32x32x16_bf16 v[0:15], v[100:103], v[16:19], v[0:15]
	ds_read_b64_tr_b16 v[16:17], v145 offset:0x200
	ds_read_b64_tr_b16 v[18:19], v145 offset:0xa00
	ds_read_b64_tr_b16 v[32:33], v145 offset:0x1200
	ds_read_b64_tr_b16 v[34:35], v145 offset:0x1a00
	ds_read_b64_tr_b16 v[36:37], v145 offset:0x2200
	ds_read_b64_tr_b16 v[38:39], v145 offset:0x2a00
	ds_read_b64_tr_b16 v[40:41], v145 offset:0x3200
	v_mfma_f32_32x32x16_bf16 v[0:15], v[104:107], v[20:23], v[0:15]
	ds_read_b64_tr_b16 v[42:43], v145 offset:0x3a00
	s_waitcnt lgkmcnt(0)
	v_mfma_f32_32x32x16_bf16 v[0:15], v[108:111], v[24:27], v[0:15]
	v_mfma_f32_32x32x16_bf16 v[16:31], v[48:51], v[16:19], 0
	v_mfma_f32_32x32x16_bf16 v[16:31], v[100:103], v[32:35], v[16:31]
	ds_read_b64_tr_b16 v[32:33], v145 offset:0x400
	ds_read_b64_tr_b16 v[34:35], v145 offset:0xc00
	ds_read_b64_tr_b16 v[52:53], v145 offset:0x1400
	ds_read_b64_tr_b16 v[54:55], v145 offset:0x1c00
	ds_read_b64_tr_b16 v[56:57], v145 offset:0x2400
	ds_read_b64_tr_b16 v[58:59], v145 offset:0x2c00
	ds_read_b64_tr_b16 v[60:61], v145 offset:0x3400
	v_mfma_f32_32x32x16_bf16 v[16:31], v[104:107], v[36:39], v[16:31]
	ds_read_b64_tr_b16 v[62:63], v145 offset:0x3c00
	s_waitcnt lgkmcnt(0)
	v_mfma_f32_32x32x16_bf16 v[16:31], v[108:111], v[40:43], v[16:31]
	v_mfma_f32_32x32x16_bf16 v[32:47], v[48:51], v[32:35], 0
	v_mfma_f32_32x32x16_bf16 v[32:47], v[100:103], v[52:55], v[32:47]
	ds_read_b64_tr_b16 v[52:53], v145 offset:0x600
	ds_read_b64_tr_b16 v[54:55], v145 offset:0xe00
	ds_read_b64_tr_b16 v[168:169], v145 offset:0x1600
	ds_read_b64_tr_b16 v[170:171], v145 offset:0x1e00
	ds_read_b64_tr_b16 v[172:173], v145 offset:0x2600
	ds_read_b64_tr_b16 v[174:175], v145 offset:0x2e00
	ds_read_b64_tr_b16 v[176:177], v145 offset:0x3600
	v_mfma_f32_32x32x16_bf16 v[32:47], v[104:107], v[56:59], v[32:47]
	ds_read_b64_tr_b16 v[178:179], v145 offset:0x3e00
	s_waitcnt lgkmcnt(0)
	v_mfma_f32_32x32x16_bf16 v[32:47], v[108:111], v[60:63], v[32:47]
	v_mfma_f32_32x32x16_bf16 v[48:63], v[48:51], v[52:55], 0
	v_max_f32_e32 v99, v81, v81
	v_mov_b32_e32 v165, 1.0
	v_mfma_f32_32x32x16_bf16 v[48:63], v[100:103], v[168:171], v[48:63]
	v_max_f32_e32 v100, v80, v80
	v_max_f32_e32 v99, v100, v99
	v_max3_f32 v99, v99, v82, v83
	v_max3_f32 v99, v99, v84, v85
	v_max3_f32 v99, v99, v86, v87
	v_max3_f32 v99, v99, v88, v89
	v_max3_f32 v99, v99, v90, v91
	v_mfma_f32_32x32x16_bf16 v[48:63], v[104:107], v[172:175], v[48:63]
	v_max3_f32 v99, v99, v92, v93
	v_max3_f32 v99, v99, v94, v95
	v_max3_f32 v99, v99, v64, v65
	v_max3_f32 v99, v99, v66, v67
	v_max3_f32 v99, v99, v68, v69
	v_max3_f32 v99, v99, v70, v71
	v_max3_f32 v99, v99, v72, v73
	v_max3_f32 v99, v99, v74, v75
	v_mfma_f32_32x32x16_bf16 v[48:63], v[108:111], v[176:179], v[48:63]
	v_max3_f32 v99, v99, v76, v77
	v_max3_f32 v99, v99, v78, v79
	v_mov_b32_e32 v100, v99
	s_nop 1
	v_permlane32_swap_b32_e32 v99, v100
	v_max_f32_e32 v100, v100, v100
	v_max_f32_e32 v99, v99, v99
	v_max_f32_e32 v99, v99, v100
	v_cmp_ge_f32_e32 vcc, s33, v99
	s_cmp_eq_u64 vcc, exec
	s_cbranch_scc0 .LBB0_457
	v_cmp_gt_u32_e64 s[34:35], 32, v97
	v_lshl_add_u32 v168, v151, 2, s29
	v_cmp_gt_f32_e32 vcc, 1.0, v165
	s_cbranch_vccz .LBB0_421
